# attn_prompt: dilation group of a workgroup's item n rotated by (blockIdx>>4)%3 so the d=1/4/16 K/V streams are spread over the loop (aprot) on top of v48
# baseline (speedup 1.0000x reference)
; __device__ __forceinline__ void attn_issue(const P& p, int it, int tid, u32x4 (&kv)[8], u32x4 (&vv)[8], bf16x8 (&qf)[4]) {
;     unsigned char* ws = p.ws;
;     const int wid = tid >> 6, lane = tid & 63, fr = lane & 15, fq = lane >> 4;
;     const int g = it >> 9, rem = it & 511, b = rem >> 8, h = (rem >> 5) & 7, sub = rem & 31;
;     const int dsh = 2 * g, d = 1 << dsh, nbs = 5 - dsh;
;     const int r = sub >> nbs, n = sub & ((1 << nbs) - 1);
;     const bf16_t* AKp = (const bf16_t*)(ws + O_AK) + (size_t)b * SEQ * 1024 + h * 128;
;     const bf16_t* AVp = (const bf16_t*)(ws + O_AV) + (size_t)b * SEQ * 1024 + h * 128;
; #pragma unroll
;     for (int ps = 0; ps < 8; ++ps) {
;         const int row = (tid >> 4) + 32 * ps, ch = tid & 15, lk = 128 * (n - 1) + row;
;         kv[ps] = (u32x4){0u, 0u, 0u, 0u}; vv[ps] = (u32x4){0u, 0u, 0u, 0u};
;         if (lk >= 0) { const size_t t = (size_t)lk * d + r; kv[ps] = *(const u32x4*)(AKp + t * 1024 + ch * 8); vv[ps] = *(const u32x4*)(AVp + t * 1024 + ch * 8); }
;     }
;     const int tq = (128 * n + 16 * wid + fr) * d + r;
;     const bf16_t* qp = (const bf16_t*)(ws + O_AQ) + ((size_t)b * SEQ + tq) * 1024 + h * 128 + fq * 8;
; #pragma unroll
;     for (int ks = 0; ks < 4; ++ks) qf[ks] = *(const bf16x8*)(qp + 32 * ks);
.LBB0_491:
	s_lshr_b32 s99, s2, 4
	s_mul_i32 s62, s99, 11
	s_lshr_b32 s62, s62, 5
	s_mul_i32 s62, s62, 3
	s_sub_u32 s99, s99, s62
	s_lshl_b32 s62, s2, 4
	s_add_u32 s0, s70, 0x152e6400
	s_addc_u32 s1, s71, 0
	s_add_u32 s28, s70, 0x182e6400
	s_addc_u32 s29, s71, 0
	s_cmpk_lt_i32 s2, 0x600
	v_mov_b32_e32 v84, v230
	s_cbranch_scc0 .LBB0_531
	s_ashr_i32 s4, s2, 8
	s_and_b32 s10, s4, -2
	s_lshl_b32 s4, s99, 1
	s_add_i32 s10, s10, s4
	s_cmp_ge_u32 s10, 6
	s_cbranch_scc0 .Lapr_p
	s_sub_i32 s10, s10, 6
.Lapr_p:
	s_and_b32 s3, s2, 31
	s_sub_i32 s5, 5, s10
	s_lshr_b32 s4, s3, s5
	s_lshl_b32 s5, -1, s5
	s_andn2_b32 s5, s3, s5
	s_add_u32 s3, s70, 0xc226400
	s_addc_u32 s23, s71, 0
	s_lshl_b32 s8, s2, 2
	s_and_b32 s6, s62, 0x1000
	s_and_b32 s8, s8, 0x380
	s_add_u32 s26, s70, 0xd266400
	s_addc_u32 s27, s71, 0
	s_lshl_b32 s11, s5, 7
	s_lshl_b32 s13, s6, 11
	s_add_u32 s9, s26, s13
	s_addc_u32 s14, s27, 0
	s_lshl_b32 s12, s8, 1
	s_add_u32 s8, s9, s12
	s_addc_u32 s9, s14, 0
	s_add_u32 s13, s3, s13
	v_lshlrev_b32_e32 v85, 3, v84
	s_addc_u32 s15, s23, 0
	v_and_b32_e32 v1, 0x78, v85
	v_mov_b32_e32 v0, 0
	s_add_u32 s14, s13, s12
	v_ashrrev_i32_e32 v130, 4, v84
	v_lshlrev_b32_e32 v124, 1, v1
	v_mov_b32_e32 v125, v0
	v_mov_b32_e32 v2, v0
	v_mov_b32_e32 v3, v0
	s_mov_b32 s7, 0
	s_addc_u32 s15, s15, 0
	v_add_u32_e32 v68, s11, v130
	v_lshl_add_u64 v[34:35], s[8:9], 0, v[124:125]
	s_movk_i32 s8, 0x7f
	v_mov_b32_e32 v1, v0
	s_waitcnt lgkmcnt(4)
	v_mov_b64_e32 v[6:7], v[2:3]
	s_waitcnt lgkmcnt(2)
	v_mov_b64_e32 v[10:11], v[2:3]
	s_mov_b32 s5, s7
	v_lshl_add_u64 v[32:33], s[14:15], 0, v[124:125]
	v_cmp_lt_i32_e32 vcc, s8, v68
	v_mov_b64_e32 v[4:5], v[0:1]
	v_mov_b64_e32 v[8:9], v[0:1]
	s_and_saveexec_b64 s[8:9], vcc
	s_cbranch_execz .LBB0_494
	v_add_u32_e32 v4, 0xffffff80, v68
	v_mov_b32_e32 v5, v0
	v_lshlrev_b64 v[4:5], s10, v[4:5]
	v_lshl_add_u64 v[4:5], v[4:5], 0, s[4:5]
	v_lshlrev_b64 v[4:5], 11, v[4:5]
	v_lshl_add_u64 v[6:7], v[32:33], 0, v[4:5]
	v_lshl_add_u64 v[8:9], v[34:35], 0, v[4:5]
	global_load_dwordx4 v[4:7], v[6:7], off
	s_nop 0
	global_load_dwordx4 v[8:11], v[8:9], off

; #define LAS __attribute__((address_space(3)))
; __device__ __forceinline__ float fexp2(float x) { return __builtin_amdgcn_exp2f(x); }
; __device__ __forceinline__ f32x4 mfma16(bf16x8 a, bf16x8 b, f32x4 c) { return __builtin_amdgcn_mfma_f32_16x16x32_bf16(a, b, c, 0, 0, 0); }
; __device__ __forceinline__ void attn_prompt_loop(const P& p, LAS unsigned char* lds, int tid, int G) {
;     ...
;     const int g = it >> 9, rem = it & 511, b = rem >> 8, h = (rem >> 5) & 7, sub = rem & 31;
;     const int dsh = 2 * g, d = 1 << dsh, nbs = 5 - dsh;
;     const int r = sub >> nbs, n = sub & ((1 << nbs) - 1);
;     __syncthreads();
; #pragma unroll
;     for (int ps = 0; ps < 8; ++ps) {
;         const int row = (tid >> 4) + 32 * ps, ch = tid & 15;
;         *(LAS u32x4*)(lds + offb(row, ch)) = kvr[ps]; *(LAS u32x4*)(lds + 65536 + offb(row, ch)) = vvr[ps];
;     }
;     const int tq = (128 * n + 16 * wid + fr) * d + r;
;     __syncthreads();
;     const int kb0 = 2 * (wid >> 1);
;     f32x4 sacc[10];
; #pragma unroll
;     for (int kbi = 0; kbi < 10; ++kbi) {
;         sacc[kbi] = (f32x4){0.f, 0.f, 0.f, 0.f};
;         const unsigned key = 16 * (kb0 + kbi) + fr;
; #pragma unroll
;         for (int ks = 0; ks < 4; ++ks) { const bf16x8 kf = *(const LAS bf16x8*)(lds + offb(key, 4 * ks + fq)); sacc[kbi] = mfma16(kf, qn[ks], sacc[kbi]); }
;     }
;     int rel = 16 * (wid & 1) + fr - 4 * fq; asm volatile("" : "+v"(rel));
;     const float slope2 = fexp2(-(float)(h + 1)) * LOG2E * (float)d;
.LBB0_510:
	v_add_u32_e32 v33, 0, v136
	s_barrier
	s_waitcnt vmcnt(5)
	ds_write_b128 v33, v[4:7]
	v_add_u32_e32 v33, s60, v136
	s_waitcnt vmcnt(4)
	ds_write_b128 v33, v[8:11]
	v_add_u32_e32 v33, 0, v137
	ds_write_b128 v33, v[0:3]
	v_add_u32_e32 v33, s60, v137
	ds_write_b128 v33, v[12:15]
	v_add_u32_e32 v33, 0, v138
	ds_write_b128 v33, v[16:19]
	v_add_u32_e32 v33, s60, v138
	ds_write_b128 v33, v[20:23]
	v_add_u32_e32 v33, 0, v139
	ds_write_b128 v33, v[24:27]
	v_add_u32_e32 v33, s60, v139
	ds_write_b128 v33, v[28:31]
	v_add_u32_e32 v33, 0, v140
	ds_write_b128 v33, v[36:39]
	v_add_u32_e32 v33, s60, v140
	ds_write_b128 v33, v[40:43]
	v_add_u32_e32 v33, 0, v141
	ds_write_b128 v33, v[44:47]
	v_add_u32_e32 v33, s60, v141
	ds_write_b128 v33, v[48:51]
	v_add_u32_e32 v33, 0, v142
	ds_write_b128 v33, v[52:55]
	v_add_u32_e32 v33, s60, v142
	ds_write_b128 v33, v[56:59]
	v_add_u32_e32 v33, 0, v143
	ds_write_b128 v33, v[60:63]
	v_add_u32_e32 v33, s60, v143
	ds_write_b128 v33, v[64:67]
	v_add_u32_e32 v33, v145, v144
	s_waitcnt lgkmcnt(0)
	s_barrier
	ds_read_b128 v[84:87], v33
	v_add_u32_e32 v34, v145, v146
	ds_read_b128 v[88:91], v34
	s_waitcnt vmcnt(0) lgkmcnt(1)
	v_mfma_f32_16x16x32_bf16 v[84:87], v[84:87], v[80:83], 0
	v_add_u32_e32 v35, v145, v147
	v_add_u32_e32 v125, v145, v148
	s_ashr_i32 s46, s86, 9
	s_add_i32 s46, s46, s99
	s_cmp_ge_u32 s46, 3
	s_cbranch_scc0 .Lapr_l
	s_sub_i32 s46, s46, 3
.Lapr_l:
	s_waitcnt lgkmcnt(0)
	v_mfma_f32_16x16x32_bf16 v[84:87], v[88:91], v[76:79], v[84:87]
	ds_read_b128 v[88:91], v35
	s_lshl_b32 s47, s46, 1
	s_sub_i32 s88, 5, s47
	s_waitcnt lgkmcnt(0)
	v_mfma_f32_16x16x32_bf16 v[84:87], v[88:91], v[72:75], v[84:87]
	ds_read_b128 v[88:91], v125
	s_bfe_u32 s87, s86, 0x30005
	s_lshl_b32 s48, -1, s88
	s_waitcnt lgkmcnt(0)
	v_mfma_f32_16x16x32_bf16 v[112:115], v[88:91], v[68:71], v[84:87]
	s_nop 2
	v_add_u32_e32 v84, v149, v144
	ds_read_b128 v[84:87], v84
	v_add_u32_e32 v88, v149, v146
	ds_read_b128 v[88:91], v88
	s_waitcnt lgkmcnt(1)
	v_mfma_f32_16x16x32_bf16 v[84:87], v[84:87], v[80:83], 0
	s_and_b32 s89, s86, 31
	s_andn2_b32 s90, s89, s48
	s_add_i32 s48, s87, 1
	s_waitcnt lgkmcnt(0)
	v_mfma_f32_16x16x32_bf16 v[84:87], v[88:91], v[76:79], v[84:87]
	v_add_u32_e32 v88, v149, v147
	ds_read_b128 v[88:91], v88
	s_lshl_b32 s30, 1, s47
	s_waitcnt lgkmcnt(0)
	v_mfma_f32_16x16x32_bf16 v[84:87], v[88:91], v[72:75], v[84:87]
	v_add_u32_e32 v88, v149, v148
	ds_read_b128 v[88:91], v88
	s_cmp_lg_u32 s90, 0
	s_waitcnt lgkmcnt(0)
	v_mfma_f32_16x16x32_bf16 v[96:99], v[88:91], v[68:71], v[84:87]
	s_nop 2
	ds_read_b128 v[84:87], v33 offset:8192
	ds_read_b128 v[88:91], v34 offset:8192
	ds_read_b128 v[120:123], v34 offset:32768
	s_waitcnt lgkmcnt(2)
	v_mfma_f32_16x16x32_bf16 v[84:87], v[84:87], v[80:83], 0
	ds_read_b128 v[192:195], v34 offset:36864
	s_waitcnt lgkmcnt(2)
	v_mfma_f32_16x16x32_bf16 v[84:87], v[88:91], v[76:79], v[84:87]
	ds_read_b128 v[88:91], v35 offset:8192
	s_waitcnt lgkmcnt(0)
	v_mfma_f32_16x16x32_bf16 v[84:87], v[88:91], v[72:75], v[84:87]
	ds_read_b128 v[88:91], v125 offset:8192
	s_waitcnt lgkmcnt(0)
	v_mfma_f32_16x16x32_bf16 v[116:119], v[88:91], v[68:71], v[84:87]
	s_nop 4
	ds_read_b128 v[84:87], v33 offset:12288
	ds_read_b128 v[88:91], v34 offset:12288
	s_waitcnt lgkmcnt(1)
	v_mfma_f32_16x16x32_bf16 v[84:87], v[84:87], v[80:83], 0
	s_waitcnt lgkmcnt(0)
	v_mfma_f32_16x16x32_bf16 v[84:87], v[88:91], v[76:79], v[84:87]
	ds_read_b128 v[88:91], v35 offset:12288
	s_waitcnt lgkmcnt(0)
	v_mfma_f32_16x16x32_bf16 v[84:87], v[88:91], v[72:75], v[84:87]
	ds_read_b128 v[88:91], v125 offset:12288
	s_waitcnt lgkmcnt(0)
	v_mfma_f32_16x16x32_bf16 v[108:111], v[88:91], v[68:71], v[84:87]
	s_nop 4
	ds_read_b128 v[84:87], v33 offset:16384
	ds_read_b128 v[88:91], v34 offset:16384
	s_waitcnt lgkmcnt(1)
	v_mfma_f32_16x16x32_bf16 v[84:87], v[84:87], v[80:83], 0
	s_waitcnt lgkmcnt(0)
	v_mfma_f32_16x16x32_bf16 v[84:87], v[88:91], v[76:79], v[84:87]
	ds_read_b128 v[88:91], v35 offset:16384
	s_waitcnt lgkmcnt(0)
	v_mfma_f32_16x16x32_bf16 v[84:87], v[88:91], v[72:75], v[84:87]
	ds_read_b128 v[88:91], v125 offset:16384
	s_waitcnt lgkmcnt(0)
	v_mfma_f32_16x16x32_bf16 v[104:107], v[88:91], v[68:71], v[84:87]
	s_nop 4
	ds_read_b128 v[84:87], v33 offset:20480
	ds_read_b128 v[88:91], v34 offset:20480
	s_waitcnt lgkmcnt(1)
	v_mfma_f32_16x16x32_bf16 v[84:87], v[84:87], v[80:83], 0
	s_waitcnt lgkmcnt(0)
	v_mfma_f32_16x16x32_bf16 v[84:87], v[88:91], v[76:79], v[84:87]
	ds_read_b128 v[88:91], v35 offset:20480
	s_waitcnt lgkmcnt(0)
	v_mfma_f32_16x16x32_bf16 v[84:87], v[88:91], v[72:75], v[84:87]
	ds_read_b128 v[88:91], v125 offset:20480
	s_waitcnt lgkmcnt(0)
	v_mfma_f32_16x16x32_bf16 v[100:103], v[88:91], v[68:71], v[84:87]
	s_nop 4
	ds_read_b128 v[84:87], v33 offset:24576
	ds_read_b128 v[88:91], v34 offset:24576
	s_waitcnt lgkmcnt(1)
	v_mfma_f32_16x16x32_bf16 v[84:87], v[84:87], v[80:83], 0
	s_waitcnt lgkmcnt(0)
	v_mfma_f32_16x16x32_bf16 v[84:87], v[88:91], v[76:79], v[84:87]
	ds_read_b128 v[88:91], v35 offset:24576
	s_waitcnt lgkmcnt(0)
	v_mfma_f32_16x16x32_bf16 v[84:87], v[88:91], v[72:75], v[84:87]
	ds_read_b128 v[88:91], v125 offset:24576
	s_waitcnt lgkmcnt(0)
	v_mfma_f32_16x16x32_bf16 v[92:95], v[88:91], v[68:71], v[84:87]
	s_nop 4
	ds_read_b128 v[84:87], v33 offset:28672
	ds_read_b128 v[88:91], v34 offset:28672
	v_cvt_f32_ubyte0_e32 v34, s48
	s_waitcnt lgkmcnt(1)
	v_mfma_f32_16x16x32_bf16 v[84:87], v[84:87], v[80:83], 0
	s_cselect_b64 s[48:49], -1, 0
	s_add_i32 s86, s86, s34
	v_exp_f32_e64 v34, -v34
	s_waitcnt lgkmcnt(0)
	v_mfma_f32_16x16x32_bf16 v[84:87], v[88:91], v[76:79], v[84:87]
	ds_read_b128 v[88:91], v35 offset:28672
	s_or_b64 s[52:53], s[6:7], s[48:49]
	v_mul_f32_e32 v34, 0x3fb8aa3b, v34
	s_waitcnt lgkmcnt(0)
; #define LAS __attribute__((address_space(3)))
; __device__ __forceinline__ float fexp2(float x) { return __builtin_amdgcn_exp2f(x); }
; __device__ __forceinline__ f32x4 mfma16(bf16x8 a, bf16x8 b, f32x4 c) { return __builtin_amdgcn_mfma_f32_16x16x32_bf16(a, b, c, 0, 0, 0); }
; __device__ __forceinline__ void attn_prompt_loop(const P& p, LAS unsigned char* lds, int tid, int G) {
;     ...
;         for (int ks = 0; ks < 4; ++ks) { const bf16x8 kf = *(const LAS bf16x8*)(lds + offb(key, 4 * ks + fq)); sacc[kbi] = mfma16(kf, qn[ks], sacc[kbi]); }
;     }
;     int rel = 16 * (wid & 1) + fr - 4 * fq; asm volatile("" : "+v"(rel));
;     const float slope2 = fexp2(-(float)(h + 1)) * LOG2E * (float)d;
;     const float c0 = -slope2 * (float)(rel + 128);
;     float mx = -INFINITY;
; #pragma unroll
;     for (int kbi = 0; kbi < 10; ++kbi) {
;         const bool blk_ok = (n > 0) || (kb0 + kbi >= 8);
; #pragma unroll
;         for (int j = 0; j < 4; ++j) {
;             bool valid = blk_ok;
;             if (kbi <= 1) valid = valid && (rel - 16 * kbi - j <= 0);
;             if (kbi >= 8) valid = valid && (rel + 128 - 16 * kbi - j >= 0);
;             const float s = valid ? sacc[kbi][j] + (c0 + slope2 * (float)(16 * kbi + j)) : -INFINITY;
;             sacc[kbi][j] = s; mx = fmaxf(mx, s);
;         }
;     }
	v_mfma_f32_16x16x32_bf16 v[84:87], v[88:91], v[72:75], v[84:87]
	ds_read_b128 v[88:91], v125 offset:28672
	s_waitcnt lgkmcnt(0)
	v_mfma_f32_16x16x32_bf16 v[88:91], v[88:91], v[68:71], v[84:87]
	s_nop 4
	ds_read_b128 v[84:87], v33 offset:32768
	s_waitcnt lgkmcnt(0)
	v_mfma_f32_16x16x32_bf16 v[84:87], v[84:87], v[80:83], 0
	v_mfma_f32_16x16x32_bf16 v[84:87], v[120:123], v[76:79], v[84:87]
	ds_read_b128 v[120:123], v35 offset:32768
	s_waitcnt lgkmcnt(0)
	v_mfma_f32_16x16x32_bf16 v[84:87], v[120:123], v[72:75], v[84:87]
	ds_read_b128 v[120:123], v125 offset:32768
	s_waitcnt lgkmcnt(0)
	v_mfma_f32_16x16x32_bf16 v[84:87], v[120:123], v[68:71], v[84:87]
	ds_read_b128 v[120:123], v33 offset:36864
	v_mov_b32_e32 v33, v132
	s_waitcnt lgkmcnt(0)
	v_mfma_f32_16x16x32_bf16 v[120:123], v[120:123], v[80:83], 0
	v_mfma_f32_16x16x32_bf16 v[120:123], v[192:195], v[76:79], v[120:123]
	ds_read_b128 v[192:195], v35 offset:36864
	v_cvt_f32_u32_e32 v35, s30
	s_mov_b32 s30, 0xff800000
	s_waitcnt lgkmcnt(0)
	v_mfma_f32_16x16x32_bf16 v[120:123], v[192:195], v[72:75], v[120:123]
	ds_read_b128 v[192:195], v125 offset:36864
	v_mul_f32_e32 v34, v34, v35
	v_add_u32_e32 v35, 0x80, v33
	v_cvt_f32_i32_e32 v35, v35
	v_cmp_gt_i32_e32 vcc, 1, v33
	s_and_b64 vcc, s[52:53], vcc
	v_add_u32_e32 v129, -2, v33
	v_mul_f32_e32 v125, v34, v35
	v_fma_f32 v127, v34, 0, -v125
	v_add_f32_e32 v112, v112, v127
	v_add_u32_e32 v127, -1, v33
	v_cndmask_b32_e32 v112, v190, v112, vcc
	v_cmp_gt_i32_e32 vcc, 1, v127
	v_fma_f32 v35, -v34, v35, v34
	s_and_b64 vcc, s[52:53], vcc
	v_add_f32_e32 v35, v113, v35
	v_cndmask_b32_e32 v35, v190, v35, vcc
	v_cmp_gt_i32_e32 vcc, 1, v129
	v_fma_f32 v191, v34, 2.0, -v125
	v_max3_f32 v113, v112, s30, v35
	s_and_b64 vcc, s[52:53], vcc
	v_add_f32_e32 v114, v114, v191
	v_add_u32_e32 v191, -3, v33
	s_mov_b32 s30, 0x40400000
	s_waitcnt lgkmcnt(0)
	v_mfma_f32_16x16x32_bf16 v[120:123], v[192:195], v[68:71], v[120:123]
	v_cndmask_b32_e32 v114, v190, v114, vcc
	v_cmp_gt_i32_e32 vcc, 1, v191
	v_fma_f32 v192, v34, s30, -v125
	s_and_b64 vcc, s[52:53], vcc
	v_add_f32_e32 v115, v115, v192
	v_add_u32_e32 v192, -16, v33
	s_mov_b32 s30, 0x41800000
	v_cndmask_b32_e32 v115, v190, v115, vcc
	s_or_b64 s[52:53], s[8:9], s[48:49]
	v_cmp_gt_i32_e32 vcc, 1, v192
	v_fma_f32 v193, v34, s30, -v125
	s_and_b64 vcc, s[52:53], vcc
	v_add_f32_e32 v96, v96, v193
	v_cndmask_b32_e32 v193, v190, v96, vcc
	v_subrev_u32_e32 v96, 17, v33
	s_mov_b32 s30, 0x41880000
	v_cmp_gt_i32_e32 vcc, 1, v96
	v_fma_f32 v194, v34, s30, -v125
	s_and_b64 vcc, s[52:53], vcc
	v_add_f32_e32 v97, v97, v194
	v_subrev_u32_e32 v194, 18, v33
	s_mov_b32 s30, 0x41900000
	v_cndmask_b32_e32 v97, v190, v97, vcc
	v_cmp_gt_i32_e32 vcc, 1, v194
	v_fma_f32 v195, v34, s30, -v125
	s_and_b64 vcc, s[52:53], vcc
	v_add_f32_e32 v98, v98, v195
	v_subrev_u32_e32 v195, 19, v33
	s_mov_b32 s30, 0x41980000
	v_cndmask_b32_e32 v98, v190, v98, vcc
	v_cmp_gt_i32_e32 vcc, 1, v195
	v_fma_f32 v196, v34, s30, -v125
	v_max3_f32 v113, v113, v114, v115
	s_and_b64 vcc, s[52:53], vcc
	v_add_f32_e32 v99, v99, v196
	v_max3_f32 v113, v113, v193, v97
	v_cndmask_b32_e32 v196, v190, v99, vcc
	s_mov_b32 s30, 0x42000000
	v_max3_f32 v99, v113, v98, v196
	v_fma_f32 v113, v34, s30, -v125
	s_mov_b32 s30, 0x42040000
	v_add_f32_e32 v113, v116, v113
	v_fma_f32 v116, v34, s30, -v125
	s_mov_b32 s30, 0x42080000
	v_add_f32_e32 v116, v117, v116
	v_fma_f32 v117, v34, s30, -v125
	s_or_b64 vcc, s[10:11], s[48:49]
	v_add_f32_e32 v117, v118, v117
	s_mov_b32 s30, 0x420c0000
	v_cndmask_b32_e32 v118, v190, v117, vcc
	v_fma_f32 v117, v34, s30, -v125
	v_add_f32_e32 v117, v119, v117
	s_mov_b32 s30, 0x42400000
	v_cndmask_b32_e32 v197, v190, v117, vcc
	v_fma_f32 v117, v34, s30, -v125
	s_mov_b32 s30, 0x42440000
	v_add_f32_e32 v108, v108, v117
	v_fma_f32 v117, v34, s30, -v125
	v_cndmask_b32_e32 v113, v190, v113, vcc
	v_cndmask_b32_e32 v116, v190, v116, vcc
	s_or_b64 vcc, s[12:13], s[48:49]
	v_add_f32_e32 v109, v109, v117
	s_mov_b32 s30, 0x42480000
	v_cndmask_b32_e32 v198, v190, v109, vcc
	v_fma_f32 v109, v34, s30, -v125
	v_add_f32_e32 v109, v110, v109
	s_mov_b32 s30, 0x424c0000
	v_cndmask_b32_e32 v199, v190, v109, vcc
	v_fma_f32 v109, v34, s30, -v125
	v_add_f32_e32 v109, v111, v109
	s_mov_b32 s30, 0x42800000
	v_cndmask_b32_e32 v111, v190, v109, vcc
	v_fma_f32 v109, v34, s30, -v125
	s_mov_b32 s30, 0x42820000
	v_add_f32_e32 v104, v104, v109
	v_fma_f32 v109, v34, s30, -v125
	s_mov_b32 s30, 0x42840000
	v_add_f32_e32 v105, v105, v109
	v_fma_f32 v109, v34, s30, -v125
	v_cndmask_b32_e32 v108, v190, v108, vcc
	s_or_b64 vcc, s[14:15], s[48:49]
	v_add_f32_e32 v106, v106, v109
	s_mov_b32 s30, 0x42860000
	v_cndmask_b32_e32 v200, v190, v106, vcc
	v_fma_f32 v106, v34, s30, -v125
	v_add_f32_e32 v106, v107, v106
	s_mov_b32 s30, 0x42a00000
	v_cndmask_b32_e32 v201, v190, v106, vcc
	v_fma_f32 v106, v34, s30, -v125
	v_cndmask_b32_e32 v104, v190, v104, vcc
	v_cndmask_b32_e32 v105, v190, v105, vcc
	s_or_b64 vcc, s[16:17], s[48:49]
	v_add_f32_e32 v100, v100, v106
	s_mov_b32 s30, 0x42a20000
	v_cndmask_b32_e32 v202, v190, v100, vcc
	v_fma_f32 v100, v34, s30, -v125
	v_add_f32_e32 v100, v101, v100
	s_mov_b32 s30, 0x42a40000
	v_cndmask_b32_e32 v203, v190, v100, vcc
	v_fma_f32 v100, v34, s30, -v125
	v_add_f32_e32 v100, v102, v100
	s_mov_b32 s30, 0x42a60000
	v_cndmask_b32_e32 v102, v190, v100, vcc
	v_fma_f32 v100, v34, s30, -v125
	v_max3_f32 v99, v99, v113, v116
	v_add_f32_e32 v100, v103, v100
	s_mov_b32 s30, 0x42c00000
	v_max3_f32 v99, v99, v118, v197
	v_cndmask_b32_e32 v204, v190, v100, vcc
	v_fma_f32 v100, v34, s30, -v125
	s_mov_b32 s30, 0x42c20000
	v_max3_f32 v99, v99, v108, v198
	v_add_f32_e32 v92, v92, v100
; __device__ __forceinline__ float fexp2(float x) { return __builtin_amdgcn_exp2f(x); }
; __device__ __forceinline__ void attn_issue(const P& p, int it, int tid, u32x4 (&kv)[8], u32x4 (&vv)[8], bf16x8 (&qf)[4]) {
;     ...
;     const int g = it >> 9, rem = it & 511, b = rem >> 8, h = (rem >> 5) & 7, sub = rem & 31;
;     const int dsh = 2 * g, d = 1 << dsh, nbs = 5 - dsh;
;     const int r = sub >> nbs, n = sub & ((1 << nbs) - 1);
; __device__ __forceinline__ void attn_prompt_loop(const P& p, LAS unsigned char* lds, int tid, int G) {
;     ...
;             bool valid = blk_ok;
;             if (kbi <= 1) valid = valid && (rel - 16 * kbi - j <= 0);
;             if (kbi >= 8) valid = valid && (rel + 128 - 16 * kbi - j >= 0);
;             const float s = valid ? sacc[kbi][j] + (c0 + slope2 * (float)(16 * kbi + j)) : -INFINITY;
;             sacc[kbi][j] = s; mx = fmaxf(mx, s);
;         }
;     }
;     mx = fmaxf(mx, __shfl_xor(mx, 16)); mx = fmaxf(mx, __shfl_xor(mx, 32));
;     float l = 0.f;
; #pragma unroll
;     for (int kbi = 0; kbi < 10; ++kbi)
; #pragma unroll
;         for (int j = 0; j < 4; ++j) { const float pe = fexp2(sacc[kbi][j] - mx); sacc[kbi][j] = pe; l += pe; }
;     l += __shfl_xor(l, 16); l += __shfl_xor(l, 32);
;     if (it + G < 1536) attn_issue(p, it + G, tid, kvr, vvr, qn);
	v_fma_f32 v100, v34, s30, -v125
	s_mov_b32 s30, 0x42c40000
	v_max3_f32 v99, v99, v199, v111
	v_add_f32_e32 v93, v93, v100
	v_fma_f32 v100, v34, s30, -v125
	s_mov_b32 s30, 0x42c60000
	v_max3_f32 v99, v99, v104, v105
	v_add_f32_e32 v94, v94, v100
	v_fma_f32 v100, v34, s30, -v125
	s_mov_b32 s30, 0x42e00000
	v_max3_f32 v99, v99, v200, v201
	v_add_f32_e32 v95, v95, v100
	v_fma_f32 v100, v34, s30, -v125
	v_max3_f32 v99, v99, v202, v203
	s_or_b64 vcc, s[18:19], s[48:49]
	v_add_f32_e32 v88, v88, v100
	s_mov_b32 s30, 0x42e20000
	v_max3_f32 v99, v99, v102, v204
	v_cndmask_b32_e32 v92, v190, v92, vcc
	v_cndmask_b32_e32 v93, v190, v93, vcc
	v_cndmask_b32_e32 v205, v190, v88, vcc
	v_fma_f32 v88, v34, s30, -v125
	v_max3_f32 v99, v99, v92, v93
	v_cndmask_b32_e32 v94, v190, v94, vcc
	v_cndmask_b32_e32 v95, v190, v95, vcc
	v_add_f32_e32 v88, v89, v88
	v_max3_f32 v99, v99, v94, v95
	v_cndmask_b32_e32 v89, v190, v88, vcc
	s_mov_b32 s30, 0x42e40000
	v_max3_f32 v88, v99, v205, v89
	v_fma_f32 v99, v34, s30, -v125
	v_add_f32_e32 v90, v90, v99
	s_mov_b32 s30, 0x42e60000
	v_cndmask_b32_e32 v206, v190, v90, vcc
	v_fma_f32 v90, v34, s30, -v125
	v_add_f32_e32 v90, v91, v90
	v_cndmask_b32_e32 v207, v190, v90, vcc
	s_or_b64 s[48:49], s[20:21], s[48:49]
	v_cmp_lt_i32_e32 vcc, -1, v33
	v_fma_f32 v33, v34, s65, -v125
	s_and_b64 vcc, s[48:49], vcc
	v_add_f32_e32 v33, v84, v33
	v_cndmask_b32_e32 v33, v190, v33, vcc
	v_cmp_lt_i32_e32 vcc, -1, v127
	v_fma_f32 v84, v34, s66, -v125
	s_and_b64 vcc, s[48:49], vcc
	v_add_f32_e32 v84, v85, v84
	v_max3_f32 v88, v88, v206, v207
	v_cndmask_b32_e32 v85, v190, v84, vcc
	v_max3_f32 v84, v88, v33, v85
	v_cmp_lt_i32_e32 vcc, -1, v129
	v_fma_f32 v88, v34, s67, -v125
	s_and_b64 vcc, s[48:49], vcc
	v_add_f32_e32 v86, v86, v88
	v_cndmask_b32_e32 v86, v190, v86, vcc
	v_cmp_lt_i32_e32 vcc, -1, v191
	v_fma_f32 v88, v34, s75, -v125
	s_and_b64 vcc, s[48:49], vcc
	v_add_f32_e32 v87, v87, v88
	v_cndmask_b32_e32 v87, v190, v87, vcc
	v_cmp_lt_i32_e32 vcc, -1, v192
	v_fma_f32 v88, v34, s76, -v125
	s_and_b64 vcc, s[48:49], vcc
	v_add_f32_e32 v88, v120, v88
	v_cndmask_b32_e32 v127, v190, v88, vcc
	v_cmp_lt_i32_e32 vcc, -1, v96
	v_fma_f32 v88, v34, s77, -v125
	s_and_b64 vcc, s[48:49], vcc
	v_add_f32_e32 v88, v121, v88
	v_cndmask_b32_e32 v191, v190, v88, vcc
	v_cmp_lt_i32_e32 vcc, -1, v194
	v_fma_f32 v88, v34, s78, -v125
	s_and_b64 vcc, s[48:49], vcc
	v_add_f32_e32 v88, v122, v88
	v_cndmask_b32_e32 v192, v190, v88, vcc
	v_cmp_lt_i32_e32 vcc, -1, v195
	v_fma_f32 v34, v34, s79, -v125
	v_and_b32_e32 v90, 64, v189
	s_and_b64 vcc, s[48:49], vcc
	v_add_f32_e32 v34, v123, v34
	v_xor_b32_e32 v88, 16, v189
	v_add_u32_e32 v90, 64, v90
	v_max3_f32 v84, v84, v86, v87
	v_cndmask_b32_e32 v34, v190, v34, vcc
	v_cmp_lt_i32_e32 vcc, v88, v90
	v_max3_f32 v84, v84, v127, v191
	v_max3_f32 v84, v84, v192, v34
	v_cndmask_b32_e32 v88, v189, v88, vcc
	v_lshlrev_b32_e32 v125, 2, v88
	ds_bpermute_b32 v88, v125, v84
	s_cmpk_gt_i32 s86, 0x5ff
	s_cselect_b64 s[48:49], -1, 0
	s_waitcnt lgkmcnt(0)
	v_max_f32_e32 v88, v88, v88
	v_max_f32_e32 v84, v84, v88
	v_xor_b32_e32 v88, 32, v189
	v_cmp_lt_i32_e32 vcc, v88, v90
	s_nop 1
	v_cndmask_b32_e32 v88, v189, v88, vcc
	v_lshlrev_b32_e32 v194, 2, v88
	ds_bpermute_b32 v88, v194, v84
	s_and_b64 vcc, exec, s[48:49]
	s_waitcnt lgkmcnt(0)
	v_max_f32_e32 v88, v88, v88
	v_max_f32_e32 v96, v84, v88
	v_sub_f32_e32 v84, v112, v96
	v_exp_f32_e32 v99, v84
	v_sub_f32_e32 v35, v35, v96
	v_exp_f32_e32 v103, v35
	v_sub_f32_e32 v33, v33, v96
	v_add_f32_e32 v84, 0, v99
	v_sub_f32_e32 v34, v34, v96
	v_add_f32_e32 v35, v103, v84
	v_sub_f32_e32 v84, v114, v96
	v_exp_f32_e32 v106, v84
	v_sub_f32_e32 v84, v115, v96
	v_exp_f32_e32 v109, v84
	v_sub_f32_e32 v84, v193, v96
	v_exp_f32_e32 v114, v84
	v_sub_f32_e32 v84, v97, v96
	v_exp_f32_e32 v117, v84
	v_sub_f32_e32 v84, v98, v96
	v_add_f32_e32 v35, v106, v35
	v_exp_f32_e32 v119, v84
	v_sub_f32_e32 v84, v196, v96
	v_add_f32_e32 v35, v109, v35
	v_exp_f32_e32 v121, v84
	v_sub_f32_e32 v84, v113, v96
	v_add_f32_e32 v35, v114, v35
	v_exp_f32_e32 v107, v84
	v_sub_f32_e32 v84, v116, v96
	v_add_f32_e32 v35, v117, v35
	v_exp_f32_e32 v110, v84
	v_sub_f32_e32 v84, v118, v96
	v_add_f32_e32 v35, v119, v35
	v_exp_f32_e32 v112, v84
	v_sub_f32_e32 v84, v197, v96
	v_add_f32_e32 v35, v121, v35
	v_exp_f32_e32 v115, v84
	v_sub_f32_e32 v84, v108, v96
	v_add_f32_e32 v35, v107, v35
	v_exp_f32_e32 v120, v84
	v_sub_f32_e32 v84, v198, v96
	v_add_f32_e32 v35, v110, v35
	v_exp_f32_e32 v122, v84
	v_sub_f32_e32 v84, v199, v96
	v_add_f32_e32 v35, v112, v35
	v_exp_f32_e32 v123, v84
	v_sub_f32_e32 v84, v111, v96
	v_add_f32_e32 v35, v115, v35
	v_exp_f32_e32 v129, v84
	v_sub_f32_e32 v84, v104, v96
	v_add_f32_e32 v35, v120, v35
	v_exp_f32_e32 v97, v84
	v_sub_f32_e32 v84, v105, v96
	v_add_f32_e32 v35, v122, v35
	v_exp_f32_e32 v100, v84
	v_sub_f32_e32 v84, v200, v96
	v_add_f32_e32 v35, v123, v35
	v_exp_f32_e32 v101, v84
	v_sub_f32_e32 v84, v201, v96
	v_add_f32_e32 v35, v129, v35
	v_exp_f32_e32 v105, v84
	v_sub_f32_e32 v84, v202, v96
	v_add_f32_e32 v35, v97, v35
	v_exp_f32_e32 v111, v84
	v_sub_f32_e32 v84, v203, v96
	v_add_f32_e32 v35, v100, v35
	v_exp_f32_e32 v113, v84
	v_sub_f32_e32 v84, v102, v96
	v_add_f32_e32 v35, v101, v35
	v_exp_f32_e32 v116, v84
	v_sub_f32_e32 v84, v204, v96
	v_add_f32_e32 v35, v105, v35
	v_exp_f32_e32 v118, v84
	v_sub_f32_e32 v84, v92, v96
	v_add_f32_e32 v35, v111, v35
	v_exp_f32_e32 v88, v84
	v_sub_f32_e32 v84, v93, v96
	v_add_f32_e32 v35, v113, v35
	v_exp_f32_e32 v90, v84
	v_sub_f32_e32 v84, v94, v96
	v_add_f32_e32 v35, v116, v35
	v_exp_f32_e32 v91, v84
	v_sub_f32_e32 v84, v95, v96
	v_add_f32_e32 v35, v118, v35
	v_exp_f32_e32 v94, v84
	v_sub_f32_e32 v84, v205, v96
	v_add_f32_e32 v35, v88, v35
	v_exp_f32_e32 v98, v84
	v_sub_f32_e32 v84, v89, v96
	v_add_f32_e32 v35, v90, v35
	v_exp_f32_e32 v102, v84
	v_sub_f32_e32 v84, v206, v96
	v_add_f32_e32 v35, v91, v35
	v_exp_f32_e32 v104, v84
	v_sub_f32_e32 v84, v207, v96
	v_add_f32_e32 v35, v94, v35
	v_exp_f32_e32 v108, v84
	v_add_f32_e32 v35, v98, v35
	v_exp_f32_e32 v84, v33
	v_add_f32_e32 v35, v102, v35
	v_add_f32_e32 v35, v104, v35
	v_add_f32_e32 v35, v108, v35
	v_add_f32_e32 v33, v84, v35
	v_sub_f32_e32 v35, v85, v96
	v_exp_f32_e32 v85, v35
	v_sub_f32_e32 v35, v86, v96
	v_exp_f32_e32 v86, v35
	v_sub_f32_e32 v35, v87, v96
	v_exp_f32_e32 v87, v35
	v_sub_f32_e32 v35, v127, v96
	v_exp_f32_e32 v89, v35
	v_sub_f32_e32 v35, v191, v96
	v_add_f32_e32 v33, v85, v33
	v_exp_f32_e32 v92, v35
	v_sub_f32_e32 v35, v192, v96
	v_add_f32_e32 v33, v86, v33
	v_exp_f32_e32 v93, v35
	v_add_f32_e32 v33, v87, v33
	v_exp_f32_e32 v95, v34
	v_add_f32_e32 v33, v89, v33
	v_add_f32_e32 v33, v92, v33
	v_add_f32_e32 v33, v93, v33
	v_add_f32_e32 v33, v95, v33
	ds_bpermute_b32 v34, v125, v33
	s_waitcnt lgkmcnt(0)
	v_add_f32_e32 v191, v33, v34
	ds_bpermute_b32 v192, v194, v191
	s_cbranch_vccnz .LBB0_528
	s_ashr_i32 s30, s86, 8
	s_and_b32 s57, s30, -2
	s_lshl_b32 s30, s99, 1
	s_add_i32 s57, s57, s30
	s_cmp_ge_u32 s57, 6
	s_cbranch_scc0 .Lapr_f
	s_sub_i32 s57, s57, 6
; __device__ __forceinline__ void attn_issue(const P& p, int it, int tid, u32x4 (&kv)[8], u32x4 (&vv)[8], bf16x8 (&qf)[4]) {
;     ...
;     const int g = it >> 9, rem = it & 511, b = rem >> 8, h = (rem >> 5) & 7, sub = rem & 31;
;     const int dsh = 2 * g, d = 1 << dsh, nbs = 5 - dsh;
;     const int r = sub >> nbs, n = sub & ((1 << nbs) - 1);
;     const bf16_t* AKp = (const bf16_t*)(ws + O_AK) + (size_t)b * SEQ * 1024 + h * 128;
;     const bf16_t* AVp = (const bf16_t*)(ws + O_AV) + (size_t)b * SEQ * 1024 + h * 128;
; #pragma unroll
;     for (int ps = 0; ps < 8; ++ps) {
;         const int row = (tid >> 4) + 32 * ps, ch = tid & 15, lk = 128 * (n - 1) + row;
;         kv[ps] = (u32x4){0u, 0u, 0u, 0u}; vv[ps] = (u32x4){0u, 0u, 0u, 0u};
;         if (lk >= 0) { const size_t t = (size_t)lk * d + r; kv[ps] = *(const u32x4*)(AKp + t * 1024 + ch * 8); vv[ps] = *(const u32x4*)(AVp + t * 1024 + ch * 8); }
;     }
;     const int tq = (128 * n + 16 * wid + fr) * d + r;
;     const bf16_t* qp = (const bf16_t*)(ws + O_AQ) + ((size_t)b * SEQ + tq) * 1024 + h * 128 + fq * 8;
; #pragma unroll
;     for (int ks = 0; ks < 4; ++ks) qf[ks] = *(const bf16x8*)(qp + 32 * ks);
.Lapr_f:
	s_and_b32 s52, s86, 31
	s_sub_i32 s53, 5, s57
	s_lshr_b32 s30, s52, s53
	s_lshl_b32 s53, -1, s53
	s_andn2_b32 s53, s52, s53
	s_add_i32 s52, s61, s85
	s_and_b32 s52, s52, 0x1000
	s_lshl_b32 s74, s52, 11
	s_add_u32 s58, s3, s74
	s_addc_u32 s59, s23, 0
	s_and_b32 s56, s63, 0x380
	s_lshl_b32 s56, s56, 1
	s_add_u32 s58, s58, s56
	s_addc_u32 s59, s59, 0
	s_add_u32 s74, s26, s74
	s_addc_u32 s91, s27, 0
	s_add_u32 s92, s74, s56
	s_addc_u32 s93, s91, 0
	s_lshl_b32 s91, s53, 7
	v_mov_b32_e32 v2, v32
	v_mov_b32_e32 v3, v32
	v_add_u32_e32 v72, s91, v133
	v_mov_b32_e32 v125, v32
	v_mov_b32_e32 v0, v32
	v_mov_b32_e32 v1, v32
	v_mov_b64_e32 v[6:7], v[2:3]
	v_mov_b64_e32 v[10:11], v[2:3]
	v_lshl_add_u64 v[68:69], s[58:59], 0, v[124:125]
	v_lshl_add_u64 v[70:71], s[92:93], 0, v[124:125]
	v_cmp_lt_i32_e32 vcc, -1, v72
	v_mov_b64_e32 v[4:5], v[0:1]
	v_mov_b64_e32 v[8:9], v[0:1]
	s_and_saveexec_b64 s[58:59], vcc
	s_cbranch_execz .LBB0_513
	v_mov_b32_e32 v73, v32
	v_lshlrev_b64 v[4:5], s57, v[72:73]
	v_lshl_add_u64 v[4:5], v[4:5], 0, s[30:31]
	v_lshlrev_b64 v[4:5], 11, v[4:5]
	v_lshl_add_u64 v[6:7], v[68:69], 0, v[4:5]
	v_lshl_add_u64 v[8:9], v[70:71], 0, v[4:5]
	global_load_dwordx4 v[4:7], v[6:7], off
	s_nop 0
	global_load_dwordx4 v[8:11], v[8:9], off

; #define LAS __attribute__((address_space(3)))
; __global__ void __launch_bounds__(NTHR) fwd_megakernel(P p) {
;     extern __shared__ __attribute__((aligned(16))) unsigned char smem[];
;     LAS unsigned char* lds = (LAS unsigned char*)smem;
	.amdhsa_kernel _Z14fwd_megakernel1P
		.amdhsa_group_segment_fixed_size 0
		.amdhsa_private_segment_fixed_size 0
		.amdhsa_kernarg_size 400
		.amdhsa_user_sgpr_count 2
		.amdhsa_user_sgpr_dispatch_ptr 0
		.amdhsa_user_sgpr_queue_ptr 0
		.amdhsa_user_sgpr_kernarg_segment_ptr 1
		.amdhsa_user_sgpr_dispatch_id 0
		.amdhsa_user_sgpr_kernarg_preload_length 0
		.amdhsa_user_sgpr_kernarg_preload_offset 0
		.amdhsa_user_sgpr_private_segment_size 0
		.amdhsa_uses_dynamic_stack 0
		.amdhsa_enable_private_segment 0
		.amdhsa_system_sgpr_workgroup_id_x 1
		.amdhsa_system_sgpr_workgroup_id_y 0
		.amdhsa_system_sgpr_workgroup_id_z 0
		.amdhsa_system_sgpr_workgroup_info 0
		.amdhsa_system_vgpr_workitem_id 2
		.amdhsa_next_free_vgpr 256
		.amdhsa_next_free_sgpr 100
		.amdhsa_accum_offset 256
		.amdhsa_reserve_vcc 1
		.amdhsa_float_round_mode_32 0
		.amdhsa_float_round_mode_16_64 0
		.amdhsa_float_denorm_mode_32 3
		.amdhsa_float_denorm_mode_16_64 3
		.amdhsa_dx10_clamp 1
		.amdhsa_ieee_mode 1
		.amdhsa_fp16_overflow 0
		.amdhsa_tg_split 0
		.amdhsa_exception_fp_ieee_invalid_op 0
		.amdhsa_exception_fp_denorm_src 0
		.amdhsa_exception_fp_ieee_div_zero 0
		.amdhsa_exception_fp_ieee_overflow 0
		.amdhsa_exception_fp_ieee_underflow 0
		.amdhsa_exception_fp_ieee_inexact 0
		.amdhsa_exception_int_div_zero 0
	.end_amdhsa_kernel

; #define LAS __attribute__((address_space(3)))
; __global__ void __launch_bounds__(NTHR) fwd_megakernel(P p) {
;     extern __shared__ __attribute__((aligned(16))) unsigned char smem[];
;     LAS unsigned char* lds = (LAS unsigned char*)smem;
.Lfunc_end0:
	.size	_Z14fwd_megakernel1P, .Lfunc_end0-_Z14fwd_megakernel1P
	.set _Z14fwd_megakernel1P.num_vgpr, 256
	.set _Z14fwd_megakernel1P.num_agpr, 0
	.set _Z14fwd_megakernel1P.numbered_sgpr, 100
	.set _Z14fwd_megakernel1P.num_named_barrier, 0
	.set _Z14fwd_megakernel1P.private_seg_size, 0
	.set _Z14fwd_megakernel1P.uses_vcc, 1
	.set _Z14fwd_megakernel1P.uses_flat_scratch, 0
	.set _Z14fwd_megakernel1P.has_dyn_sized_stack, 0
	.set _Z14fwd_megakernel1P.has_recursion, 0
	.set _Z14fwd_megakernel1P.has_indirect_call, 0

amdhsa.kernels:
  - .agpr_count:     0
    .args:
      - .offset:         0
        .size:           144
        .value_kind:     by_value
      - .offset:         144
        .size:           4
        .value_kind:     hidden_block_count_x
      - .offset:         148
        .size:           4
        .value_kind:     hidden_block_count_y
      - .offset:         152
        .size:           4
        .value_kind:     hidden_block_count_z
      - .offset:         156
        .size:           2
        .value_kind:     hidden_group_size_x
      - .offset:         158
        .size:           2
        .value_kind:     hidden_group_size_y
      - .offset:         160
        .size:           2
        .value_kind:     hidden_group_size_z
      - .offset:         162
        .size:           2
        .value_kind:     hidden_remainder_x
      - .offset:         164
        .size:           2
        .value_kind:     hidden_remainder_y
      - .offset:         166
        .size:           2
        .value_kind:     hidden_remainder_z
      - .offset:         184
        .size:           8
        .value_kind:     hidden_global_offset_x
      - .offset:         192
        .size:           8
        .value_kind:     hidden_global_offset_y
      - .offset:         200
        .size:           8
        .value_kind:     hidden_global_offset_z
      - .offset:         208
        .size:           2
        .value_kind:     hidden_grid_dims
      - .offset:         232
        .size:           8
        .value_kind:     hidden_multigrid_sync_arg
      - .offset:         264
        .size:           4
        .value_kind:     hidden_dynamic_lds_size
    .group_segment_fixed_size: 0
    .kernarg_segment_align: 8
    .kernarg_segment_size: 400
    .language:       OpenCL C
    .language_version:
      - 2
      - 0
    .max_flat_workgroup_size: 512
    .name:           _Z14fwd_megakernel1P
    .private_segment_fixed_size: 0
    .sgpr_count:     106
    .sgpr_spill_count: 25
    .symbol:         _Z14fwd_megakernel1P.kd
    .uniform_work_group_size: 1
    .uses_dynamic_stack: false
    .vgpr_count:     256
    .vgpr_spill_count: 0
    .wavefront_size: 64
